# combo23 + E64: ssd_pass2 epilogue tail issues its 16 norm-weight loads together (into registers dead in the tail) with counted waits, instead of 8 load-pair -> full-drain -> scale -> store chains that
# speedup vs baseline: 1.0109x; 1.0109x over previous
.LBB0_220:
	s_waitcnt vmcnt(9)
	v_add_u32_e32 v0, s19, v169
	v_ashrrev_i32_e32 v1, 31, v0
	v_readlane_b32 s0, v251, 24
	v_lshlrev_b64 v[108:109], 12, v[0:1]
	v_readlane_b32 s1, v251, 25
	s_ashr_i32 s35, s34, 31
	v_readlane_b32 s40, v254, 20
	v_lshl_add_u64 v[0:1], s[0:1], 0, v[108:109]
	s_lshl_b32 s28, s17, 1
	s_lshl_b64 s[0:1], s[34:35], 2
	v_readlane_b32 s50, v254, 30
	v_lshl_add_u64 v[0:1], v[0:1], 0, s[28:29]
	v_mov_b32_e32 v133, v157
	v_readlane_b32 s51, v254, 31
	s_add_u32 s0, s50, s0
	v_lshl_add_u64 v[0:1], v[0:1], 0, v[132:133]
	s_addc_u32 s1, s51, s1
	global_load_dwordx4 v[28:31], v[0:1], off
	global_load_dwordx4 v[24:27], v[0:1], off offset:128
	global_load_dwordx4 v[20:23], v[0:1], off offset:256
	global_load_dwordx4 v[16:19], v[0:1], off offset:384
	global_load_dwordx4 v[12:15], v[0:1], off offset:512
	global_load_dwordx4 v[8:11], v[0:1], off offset:640
	global_load_dwordx4 v[4:7], v[0:1], off offset:768
	s_nop 0
	global_load_dwordx4 v[0:3], v[0:1], off offset:896
	v_cmp_lt_i32_e32 vcc, v188, v187
	global_load_dword v110, v157, s[0:1]
	v_readlane_b32 s0, v253, 62
	s_mov_b32 s56, 0x800000
	v_readlane_b32 s52, v254, 32
	v_add3_u32 v112, s0, v173, v137
	ds_read2_b64 v[104:107], v112 offset1:4
	v_add_u32_e32 v113, 0x1000, v112
	v_add_u32_e32 v118, 0x1800, v112
	s_lshl_b32 s0, s20, 2
	s_add_i32 s0, s0, 16
	s_waitcnt vmcnt(10) lgkmcnt(0)
	v_lshlrev_b32_e32 v32, 16, v104
	v_readlane_b32 s53, v254, 33
	v_readlane_b32 s8, v251, 51
	v_readlane_b32 s9, v251, 52
	v_readlane_b32 s72, v254, 41
	v_readlane_b32 s54, v254, 34
	v_readlane_b32 s55, v254, 35
	v_readlane_b32 s70, v254, 39
	v_readlane_b32 s73, v254, 42
	v_readlane_b32 s74, v254, 44
	v_readlane_b32 s76, v254, 46
	v_readlane_b32 s78, v254, 48
	v_readlane_b32 s82, v254, 52
	v_readlane_b32 s60, v254, 54
	v_readlane_b32 s62, v254, 56
	v_readlane_b32 s64, v254, 58
	v_readlane_b32 s66, v254, 60
	s_movk_i32 s68, 0x2040
	v_readlane_b32 s57, v254, 36
	v_readlane_b32 s58, v254, 37
	v_readlane_b32 s59, v254, 38
	v_readlane_b32 s71, v254, 40
	v_readlane_b32 s69, v254, 43
	v_readlane_b32 s75, v254, 45
	v_readlane_b32 s77, v254, 47
	v_readlane_b32 s79, v254, 49
	v_readlane_b32 s80, v254, 50
	v_readlane_b32 s81, v254, 51
	v_readlane_b32 s83, v254, 53
	v_readlane_b32 s61, v254, 55
	v_readlane_b32 s63, v254, 57
	v_readlane_b32 s65, v254, 59
	v_readlane_b32 s67, v254, 61
	s_movk_i32 s73, 0xf5
	s_movk_i32 s55, 0xfff
	s_mov_b32 s54, 0xf0c0
	v_readlane_b32 s41, v254, 21
	v_readlane_b32 s42, v254, 22
	v_readlane_b32 s43, v254, 23
	v_readlane_b32 s44, v254, 24
	v_readlane_b32 s45, v254, 25
	v_readlane_b32 s46, v254, 26
	v_readlane_b32 s47, v254, 27
	v_readlane_b32 s48, v254, 28
	v_readlane_b32 s49, v254, 29
	s_waitcnt vmcnt(0)
	v_fma_f32 v111, v110, v32, v40
	v_and_b32_e32 v32, 0xffff0000, v104
	v_fma_f32 v104, v110, v32, v41
	v_lshlrev_b32_e32 v32, 16, v105
	v_fma_f32 v42, v110, v32, v42
	v_and_b32_e32 v32, 0xffff0000, v105
	v_add_u32_e32 v105, 0x800, v112
	ds_read2_b64 v[34:37], v105 offset0:32 offset1:36
	ds_read2_b64 v[38:41], v113 offset0:64 offset1:68
	v_fmac_f32_e32 v43, v110, v32
	ds_read2_b64 v[114:117], v105 offset0:40 offset1:44
	s_waitcnt lgkmcnt(2)
	v_lshlrev_b32_e32 v32, 16, v34
	v_fma_f32 v48, v110, v32, v48
	v_and_b32_e32 v32, 0xffff0000, v34
	v_fma_f32 v49, v110, v32, v49
	v_lshlrev_b32_e32 v32, 16, v35
	v_fma_f32 v50, v110, v32, v50
	v_and_b32_e32 v32, 0xffff0000, v35
	v_fmac_f32_e32 v51, v110, v32
	s_waitcnt lgkmcnt(1)
	v_lshlrev_b32_e32 v32, 16, v38
	v_fma_f32 v44, v110, v32, v44
	v_and_b32_e32 v32, 0xffff0000, v38
	v_fma_f32 v38, v110, v32, v45
	v_lshlrev_b32_e32 v32, 16, v39
	v_fma_f32 v45, v110, v32, v46
	v_and_b32_e32 v32, 0xffff0000, v39
	v_fmac_f32_e32 v47, v110, v32
	ds_read2_b64 v[32:35], v118 offset0:96 offset1:100
	ds_read2_b64 v[118:121], v118 offset0:104 offset1:108
	s_waitcnt lgkmcnt(1)
	v_lshlrev_b32_e32 v46, 16, v33
	v_fma_f32 v46, v110, v46, v54
	v_and_b32_e32 v33, 0xffff0000, v33
	v_and_b32_e32 v54, 0xffff0000, v107
	v_lshlrev_b32_e32 v39, 16, v32
	v_fmac_f32_e32 v55, v110, v33
	v_lshlrev_b32_e32 v33, 16, v106
	v_fmac_f32_e32 v59, v110, v54
	v_lshlrev_b32_e32 v54, 16, v36
	v_and_b32_e32 v36, 0xffff0000, v36
	v_fma_f32 v39, v110, v39, v52
	v_fma_f32 v33, v110, v33, v56
	v_and_b32_e32 v52, 0xffff0000, v106
	v_fma_f32 v56, v110, v36, v61
	v_lshlrev_b32_e32 v36, 16, v37
	v_and_b32_e32 v32, 0xffff0000, v32
	v_fma_f32 v52, v110, v52, v57
	v_fma_f32 v57, v110, v36, v62
	v_and_b32_e32 v36, 0xffff0000, v37
	v_fma_f32 v32, v110, v32, v53
	v_lshlrev_b32_e32 v53, 16, v107
	v_fmac_f32_e32 v63, v110, v36
	v_lshlrev_b32_e32 v36, 16, v40
	v_fma_f32 v53, v110, v53, v58
	v_fma_f32 v58, v110, v36, v64
	v_and_b32_e32 v36, 0xffff0000, v40
	v_fma_f32 v40, v110, v36, v65
	v_lshlrev_b32_e32 v36, 16, v41
	v_fma_f32 v54, v110, v54, v60
	v_fma_f32 v60, v110, v36, v66
	v_and_b32_e32 v36, 0xffff0000, v41
	v_fmac_f32_e32 v67, v110, v36
	v_lshlrev_b32_e32 v36, 16, v34
	v_and_b32_e32 v34, 0xffff0000, v34
	v_fma_f32 v61, v110, v34, v81
	v_lshlrev_b32_e32 v34, 16, v35
	v_fma_f32 v62, v110, v34, v82
	v_and_b32_e32 v34, 0xffff0000, v35
	v_fma_f32 v41, v110, v36, v80
	v_fmac_f32_e32 v83, v110, v34
	ds_read2_b64 v[34:37], v112 offset0:8 offset1:12
	v_and_b32_e32 v66, 0xffff0000, v114
	v_fma_f32 v66, v110, v66, v73
	v_and_b32_e32 v73, 0xffff0000, v115
	v_and_b32_e32 v80, 0xffff0000, v116
	s_waitcnt lgkmcnt(0)
	v_lshlrev_b32_e32 v65, 16, v35
	v_fma_f32 v65, v110, v65, v78
	v_lshlrev_b32_e32 v78, 16, v37
	v_fma_f32 v78, v110, v78, v90
	v_and_b32_e32 v37, 0xffff0000, v37
	v_and_b32_e32 v90, 0xffff0000, v121
	v_and_b32_e32 v35, 0xffff0000, v35
	v_fmac_f32_e32 v91, v110, v37
	v_lshlrev_b32_e32 v37, 16, v116
	v_fmac_f32_e32 v103, v110, v90
	v_lshl_add_u32 v90, v171, 2, s0
	s_movk_i32 s0, 0x2040
	v_fmac_f32_e32 v79, v110, v35
	v_lshlrev_b32_e32 v35, 16, v114
	v_fma_f32 v37, v110, v37, v92
	v_mad_u32_u24 v92, v172, s0, v90
	v_fma_f32 v35, v110, v35, v72
	v_lshlrev_b32_e32 v72, 16, v115
	ds_read2_b64 v[112:115], v113 offset0:72 offset1:76
	s_waitcnt lgkmcnt(0)
	s_barrier
	ds_write2_b32 v92, v111, v48 offset1:16
	v_add_u32_e32 v48, 0x800, v92
	ds_write2_b32 v48, v104, v49 offset0:4 offset1:20
	v_add_u32_e32 v49, 0x1000, v92
	ds_write2_b32 v49, v42, v50 offset0:8 offset1:24
	v_add_u32_e32 v42, 0x1800, v92
	ds_write2_b32 v42, v43, v51 offset0:12 offset1:28
	ds_write2_b32 v92, v44, v39 offset0:32 offset1:48
	ds_write2_b32 v48, v38, v32 offset0:36 offset1:52
	ds_write2_b32 v49, v45, v46 offset0:40 offset1:56
	ds_write2_b32 v42, v47, v55 offset0:44 offset1:60
	v_add_u32_e32 v32, 0x8000, v92
	ds_write2_b32 v32, v33, v54 offset0:64 offset1:80
	v_add_u32_e32 v33, 0x8800, v92
	v_add_u32_e32 v38, 0x9000, v92
	v_add_u32_e32 v39, 0x9800, v92
	ds_write2_b32 v33, v52, v56 offset0:68 offset1:84
	ds_write2_b32 v38, v53, v57 offset0:72 offset1:88
	ds_write2_b32 v39, v59, v63 offset0:76 offset1:92
	ds_write2_b32 v32, v58, v41 offset0:96 offset1:112
	ds_write2_b32 v33, v40, v61 offset0:100 offset1:116
	ds_write2_b32 v38, v60, v62 offset0:104 offset1:120
	ds_write2_b32 v39, v67, v83 offset0:108 offset1:124
	v_mov_b32_e32 v32, 0x10200
	v_lshlrev_b32_e32 v64, 16, v34
	v_mad_u32_u24 v32, v172, s0, v32
	v_fma_f32 v64, v110, v64, v76
	v_add_u32_e32 v33, v90, v32
	ds_write_b32 v33, v64
	v_mov_b32_e32 v33, 0x10a10
	v_and_b32_e32 v34, 0xffff0000, v34
	v_mad_u32_u24 v33, v172, s0, v33
	v_fma_f32 v34, v110, v34, v77
	v_add_u32_e32 v38, v90, v33
	ds_write_b32 v38, v34
	v_mov_b32_e32 v34, 0x11220
	v_mad_u32_u24 v34, v172, s0, v34
	v_add_u32_e32 v38, v90, v34
	ds_write_b32 v38, v65
	v_mov_b32_e32 v38, 0x11a30
	v_mad_u32_u24 v38, v172, s0, v38
	v_fmac_f32_e32 v75, v110, v73
	v_lshlrev_b32_e32 v73, 16, v112
	v_fma_f32 v80, v110, v80, v93
	v_add_u32_e32 v93, 64, v90
	v_add_u32_e32 v39, v90, v38
	v_fma_f32 v68, v110, v73, v68
	v_and_b32_e32 v73, 0xffff0000, v112
	ds_write_b32 v39, v79
	v_add_u32_e32 v39, v93, v32
	v_fma_f32 v69, v110, v73, v69
	v_lshlrev_b32_e32 v73, 16, v113
	ds_write_b32 v39, v35
	v_add_u32_e32 v35, v93, v33
	v_fma_f32 v72, v110, v72, v74
	v_fma_f32 v70, v110, v73, v70
	v_and_b32_e32 v73, 0xffff0000, v113
	ds_write_b32 v35, v66
	v_add_u32_e32 v35, v93, v34
	v_fmac_f32_e32 v71, v110, v73
	v_lshlrev_b32_e32 v73, 16, v118
	v_add_u32_e32 v43, 0x80, v90
	v_add_u32_e32 v50, 0xc0, v90
	ds_write_b32 v35, v72
	v_add_u32_e32 v35, v93, v38
	v_fma_f32 v73, v110, v73, v84
	v_and_b32_e32 v74, 0xffff0000, v118
	ds_write_b32 v35, v75
	v_add_u32_e32 v35, v43, v32
	v_add_u32_e32 v32, v50, v32
	v_fma_f32 v74, v110, v74, v85
	v_lshlrev_b32_e32 v76, 16, v119
	ds_write_b32 v32, v73
	v_add_u32_e32 v32, v50, v33
	v_fma_f32 v76, v110, v76, v86
	v_and_b32_e32 v77, 0xffff0000, v119
	ds_write_b32 v32, v74
	v_add_u32_e32 v32, v50, v34
	v_fmac_f32_e32 v87, v110, v77
	ds_write_b32 v32, v76
	v_add_u32_e32 v32, v50, v38
	ds_write_b32 v32, v87
	v_mov_b32_e32 v32, 0x18300
	v_lshlrev_b32_e32 v77, 16, v36
	v_mad_u32_u24 v32, v172, s0, v32
	v_fma_f32 v77, v110, v77, v88
	ds_write_b32 v35, v68
	v_add_u32_e32 v35, v43, v33
	v_add_u32_e32 v33, v90, v32
	ds_write_b32 v33, v77
	v_mov_b32_e32 v33, 0x18b10
	v_and_b32_e32 v36, 0xffff0000, v36
	v_mad_u32_u24 v33, v172, s0, v33
	v_fma_f32 v36, v110, v36, v89
	ds_write_b32 v35, v69
	v_add_u32_e32 v35, v43, v34
	v_add_u32_e32 v34, v90, v33
	ds_write_b32 v34, v36
	v_mov_b32_e32 v34, 0x19320
	ds_write_b32 v35, v70
	v_add_u32_e32 v35, v43, v38
	v_mad_u32_u24 v34, v172, s0, v34
	ds_write_b32 v35, v71
	v_add_u32_e32 v35, v90, v34
	ds_write_b32 v35, v78
	v_mad_u32_u24 v35, v172, s0, v198
	v_add_u32_e32 v36, v90, v35
	ds_write_b32 v36, v91
	v_add_u32_e32 v36, v93, v32
	v_lshlrev_b32_e32 v81, 16, v117
	ds_write_b32 v36, v37
	v_add_u32_e32 v36, v93, v33
	v_fma_f32 v81, v110, v81, v94
	v_and_b32_e32 v82, 0xffff0000, v117
	v_and_b32_e32 v86, 0xffff0000, v115
	ds_write_b32 v36, v80
	v_add_u32_e32 v36, v93, v34
	v_fmac_f32_e32 v95, v110, v82
	v_fmac_f32_e32 v99, v110, v86
	v_lshlrev_b32_e32 v86, 16, v120
	ds_write_b32 v36, v81
	v_add_u32_e32 v36, v93, v35
	v_fma_f32 v86, v110, v86, v100
	v_and_b32_e32 v88, 0xffff0000, v120
	ds_write_b32 v36, v95
	v_add_u32_e32 v36, v43, v32
	v_add_u32_e32 v32, v50, v32
	v_lshlrev_b32_e32 v82, 16, v114
	v_fma_f32 v88, v110, v88, v101
	v_lshlrev_b32_e32 v89, 16, v121
	ds_write_b32 v32, v86
	v_add_u32_e32 v32, v50, v33
	v_fma_f32 v82, v110, v82, v96
	v_and_b32_e32 v84, 0xffff0000, v114
	v_fma_f32 v89, v110, v89, v102
	ds_write_b32 v32, v88
	v_add_u32_e32 v32, v50, v34
	v_fma_f32 v84, v110, v84, v97
	v_lshlrev_b32_e32 v85, 16, v115
	ds_write_b32 v36, v82
	v_add_u32_e32 v36, v43, v33
	ds_write_b32 v32, v89
	v_add_u32_e32 v32, v50, v35
	s_movk_i32 s0, 0x810
	v_fma_f32 v85, v110, v85, v98
	ds_write_b32 v36, v84
	v_add_u32_e32 v36, v43, v34
	ds_write_b32 v32, v103
	v_mul_lo_u32 v33, v169, s0
	v_lshlrev_b32_e32 v32, 2, v166
	ds_write_b32 v36, v85
	v_add_u32_e32 v36, v43, v35
	v_add3_u32 v76, 16, v33, v32
	ds_write_b32 v36, v99
	s_waitcnt lgkmcnt(0)
	s_barrier
	ds_read_b128 v[34:37], v76
	ds_read_b128 v[38:41], v76 offset:16
	v_lshlrev_b32_e32 v33, 16, v28
	v_and_b32_e32 v28, 0xffff0000, v28
	v_lshlrev_b32_e32 v42, 16, v29
	s_waitcnt lgkmcnt(1)
	v_mul_f32_e32 v72, v35, v28
	v_mul_f32_e32 v73, v34, v33
	v_mul_f32_e32 v77, v72, v72
	v_and_b32_e32 v29, 0xffff0000, v29
	v_mul_f32_e32 v71, v36, v42
	v_fmac_f32_e32 v77, v73, v73
	v_lshlrev_b32_e32 v43, 16, v30
	v_and_b32_e32 v30, 0xffff0000, v30
	v_lshlrev_b32_e32 v44, 16, v31
	v_and_b32_e32 v31, 0xffff0000, v31
	v_mul_f32_e32 v70, v37, v29
	v_fmac_f32_e32 v77, v71, v71
	s_waitcnt lgkmcnt(0)
	v_mul_f32_e32 v69, v38, v43
	v_mul_f32_e32 v68, v39, v30
	v_mul_f32_e32 v65, v41, v31
	v_fmac_f32_e32 v77, v70, v70
	ds_read_b128 v[28:31], v76 offset:256
	ds_read_b128 v[34:37], v76 offset:272
	v_fmac_f32_e32 v77, v69, v69
	v_mul_f32_e32 v67, v40, v44
	v_fmac_f32_e32 v77, v68, v68
	v_fmac_f32_e32 v77, v67, v67
	v_lshlrev_b32_e32 v33, 16, v24
	v_fmac_f32_e32 v77, v65, v65
	v_and_b32_e32 v24, 0xffff0000, v24
	s_waitcnt lgkmcnt(1)
	v_mul_f32_e32 v66, v28, v33
	v_lshlrev_b32_e32 v38, 16, v25
	v_mul_f32_e32 v63, v29, v24
	v_fmac_f32_e32 v77, v66, v66
	v_and_b32_e32 v25, 0xffff0000, v25
	v_mul_f32_e32 v60, v30, v38
	v_fmac_f32_e32 v77, v63, v63
	v_lshlrev_b32_e32 v39, 16, v26
	v_and_b32_e32 v26, 0xffff0000, v26
	v_lshlrev_b32_e32 v40, 16, v27
	v_and_b32_e32 v27, 0xffff0000, v27
	v_mul_f32_e32 v56, v31, v25
	v_fmac_f32_e32 v77, v60, v60
	s_waitcnt lgkmcnt(0)
	v_mul_f32_e32 v51, v34, v39
	v_mul_f32_e32 v45, v35, v26
	v_mul_f32_e32 v35, v37, v27
	v_fmac_f32_e32 v77, v56, v56
	ds_read_b128 v[24:27], v76 offset:512
	ds_read_b128 v[28:31], v76 offset:528
	v_fmac_f32_e32 v77, v51, v51
	v_mul_f32_e32 v40, v36, v40
	v_fmac_f32_e32 v77, v45, v45
	v_fmac_f32_e32 v77, v40, v40
	v_lshlrev_b32_e32 v33, 16, v20
	v_fmac_f32_e32 v77, v35, v35
	v_and_b32_e32 v20, 0xffff0000, v20
	s_waitcnt lgkmcnt(1)
	v_mul_f32_e32 v64, v24, v33
	v_lshlrev_b32_e32 v34, 16, v21
	v_mul_f32_e32 v61, v25, v20
	v_fmac_f32_e32 v77, v64, v64
	v_and_b32_e32 v21, 0xffff0000, v21
	v_mul_f32_e32 v57, v26, v34
	v_fmac_f32_e32 v77, v61, v61
	v_lshlrev_b32_e32 v36, 16, v22
	v_and_b32_e32 v22, 0xffff0000, v22
	v_lshlrev_b32_e32 v37, 16, v23
	v_and_b32_e32 v23, 0xffff0000, v23
	v_mul_f32_e32 v52, v27, v21
	v_fmac_f32_e32 v77, v57, v57
	s_waitcnt lgkmcnt(0)
	v_mul_f32_e32 v46, v28, v36
	v_mul_f32_e32 v41, v29, v22
	v_mul_f32_e32 v36, v30, v37
	v_mul_f32_e32 v30, v31, v23
	v_fmac_f32_e32 v77, v52, v52
	ds_read_b128 v[20:23], v76 offset:768
	ds_read_b128 v[24:27], v76 offset:784
	v_fmac_f32_e32 v77, v46, v46
	v_fmac_f32_e32 v77, v41, v41
	v_fmac_f32_e32 v77, v36, v36
	v_lshlrev_b32_e32 v28, 16, v16
	v_fmac_f32_e32 v77, v30, v30
	v_and_b32_e32 v16, 0xffff0000, v16
	s_waitcnt lgkmcnt(1)
	v_mul_f32_e32 v62, v20, v28
	v_lshlrev_b32_e32 v29, 16, v17
	v_mul_f32_e32 v58, v21, v16
	v_fmac_f32_e32 v77, v62, v62
	v_and_b32_e32 v17, 0xffff0000, v17
	v_mul_f32_e32 v53, v22, v29
	v_fmac_f32_e32 v77, v58, v58
	v_lshlrev_b32_e32 v31, 16, v18
	v_and_b32_e32 v18, 0xffff0000, v18
	v_lshlrev_b32_e32 v33, 16, v19
	v_and_b32_e32 v19, 0xffff0000, v19
	v_mul_f32_e32 v47, v23, v17
	v_fmac_f32_e32 v77, v53, v53
	s_waitcnt lgkmcnt(0)
	v_mul_f32_e32 v42, v24, v31
	v_mul_f32_e32 v37, v25, v18
	v_mul_f32_e32 v27, v27, v19
	v_fmac_f32_e32 v77, v47, v47
	ds_read_b128 v[16:19], v76 offset:1024
	ds_read_b128 v[20:23], v76 offset:1040
	v_fmac_f32_e32 v77, v42, v42
	v_mul_f32_e32 v31, v26, v33
	v_fmac_f32_e32 v77, v37, v37
	v_fmac_f32_e32 v77, v31, v31
	v_lshlrev_b32_e32 v24, 16, v12
	v_fmac_f32_e32 v77, v27, v27
	v_and_b32_e32 v12, 0xffff0000, v12
	s_waitcnt lgkmcnt(1)
	v_mul_f32_e32 v59, v16, v24
	v_lshlrev_b32_e32 v25, 16, v13
	v_mul_f32_e32 v54, v17, v12
	v_fmac_f32_e32 v77, v59, v59
	v_and_b32_e32 v13, 0xffff0000, v13
	v_mul_f32_e32 v48, v18, v25
	v_fmac_f32_e32 v77, v54, v54
	v_lshlrev_b32_e32 v26, 16, v14
	v_and_b32_e32 v14, 0xffff0000, v14
	v_lshlrev_b32_e32 v28, 16, v15
	v_and_b32_e32 v15, 0xffff0000, v15
	v_mul_f32_e32 v43, v19, v13
	v_fmac_f32_e32 v77, v48, v48
	s_waitcnt lgkmcnt(0)
	v_mul_f32_e32 v38, v20, v26
	v_mul_f32_e32 v33, v21, v14
	v_mul_f32_e32 v24, v23, v15
	v_fmac_f32_e32 v77, v43, v43
	ds_read_b128 v[12:15], v76 offset:1280
	ds_read_b128 v[16:19], v76 offset:1296
	v_fmac_f32_e32 v77, v38, v38
	v_mul_f32_e32 v28, v22, v28
	v_fmac_f32_e32 v77, v33, v33
	v_fmac_f32_e32 v77, v28, v28
	v_lshlrev_b32_e32 v20, 16, v8
	v_fmac_f32_e32 v77, v24, v24
	v_and_b32_e32 v8, 0xffff0000, v8
	s_waitcnt lgkmcnt(1)
	v_mul_f32_e32 v55, v12, v20
	v_lshlrev_b32_e32 v21, 16, v9
	v_mul_f32_e32 v49, v13, v8
	v_fmac_f32_e32 v77, v55, v55
	v_and_b32_e32 v9, 0xffff0000, v9
	v_mul_f32_e32 v44, v14, v21
	v_fmac_f32_e32 v77, v49, v49
	v_lshlrev_b32_e32 v22, 16, v10
	v_and_b32_e32 v10, 0xffff0000, v10
	v_lshlrev_b32_e32 v23, 16, v11
	v_and_b32_e32 v11, 0xffff0000, v11
	v_mul_f32_e32 v39, v15, v9
	v_fmac_f32_e32 v77, v44, v44
	s_waitcnt lgkmcnt(0)
	v_mul_f32_e32 v34, v16, v22
	v_mul_f32_e32 v29, v17, v10
	v_mul_f32_e32 v25, v18, v23
	v_mul_f32_e32 v23, v19, v11
	v_fmac_f32_e32 v77, v39, v39
	ds_read_b128 v[8:11], v76 offset:1536
	ds_read_b128 v[12:15], v76 offset:1552
	v_fmac_f32_e32 v77, v34, v34
	v_fmac_f32_e32 v77, v29, v29
	v_fmac_f32_e32 v77, v25, v25
	v_lshlrev_b32_e32 v16, 16, v4
	v_fmac_f32_e32 v77, v23, v23
	v_and_b32_e32 v4, 0xffff0000, v4
	s_waitcnt lgkmcnt(1)
	v_mul_f32_e32 v50, v8, v16
	v_lshlrev_b32_e32 v17, 16, v5
	v_and_b32_e32 v5, 0xffff0000, v5
	v_lshlrev_b32_e32 v18, 16, v6
	v_and_b32_e32 v6, 0xffff0000, v6
	v_lshlrev_b32_e32 v74, 16, v7
	v_and_b32_e32 v7, 0xffff0000, v7
	v_mul_f32_e32 v26, v9, v4
	v_fmac_f32_e32 v77, v50, v50
	v_mul_f32_e32 v22, v10, v17
	v_mul_f32_e32 v21, v11, v5
	s_waitcnt lgkmcnt(0)
	v_mul_f32_e32 v20, v12, v18
	v_mul_f32_e32 v19, v13, v6
	v_mul_f32_e32 v18, v14, v74
	v_mul_f32_e32 v17, v15, v7
	v_fmac_f32_e32 v77, v26, v26
	v_lshlrev_b32_e32 v4, 16, v0
	v_and_b32_e32 v5, 0xffff0000, v0
	v_lshlrev_b32_e32 v6, 16, v1
	v_and_b32_e32 v7, 0xffff0000, v1
	v_lshlrev_b32_e32 v8, 16, v2
	v_and_b32_e32 v9, 0xffff0000, v2
	v_lshlrev_b32_e32 v74, 16, v3
	v_and_b32_e32 v75, 0xffff0000, v3
	ds_read_b128 v[0:3], v76 offset:1792
	v_fmac_f32_e32 v77, v22, v22
	v_fmac_f32_e32 v77, v21, v21
	v_fmac_f32_e32 v77, v20, v20
	v_fmac_f32_e32 v77, v19, v19
	v_fmac_f32_e32 v77, v18, v18
	s_waitcnt lgkmcnt(0)
	v_pk_mul_f32 v[14:15], v[0:1], v[4:5]
	v_fmac_f32_e32 v77, v17, v17
	v_pk_mul_f32 v[0:1], v[14:15], v[14:15]
	v_pk_mul_f32 v[12:13], v[2:3], v[6:7]
	v_add_f32_e32 v0, v77, v0
	v_add_f32_e32 v4, v0, v1
	v_pk_mul_f32 v[0:1], v[12:13], v[12:13]
	s_lshl_b32 s0, s17, 2
	v_add_f32_e32 v0, v4, v0
	v_add_f32_e32 v4, v0, v1
	ds_read_b128 v[0:3], v76 offset:1808
	s_add_u32 s0, s52, s0
	s_addc_u32 s1, s53, 0
	s_waitcnt lgkmcnt(0)
	v_pk_mul_f32 v[10:11], v[0:1], v[8:9]
	s_nop 0
	v_pk_mul_f32 v[0:1], v[10:11], v[10:11]
	v_pk_mul_f32 v[8:9], v[2:3], v[74:75]
	v_add_f32_e32 v0, v4, v0
	v_add_f32_e32 v4, v0, v1
	v_pk_mul_f32 v[0:1], v[8:9], v[8:9]
	s_nop 0
	v_add_f32_e32 v0, v4, v0
	v_add_f32_e32 v0, v0, v1
	v_cndmask_b32_e32 v1, v185, v188, vcc
	v_lshlrev_b32_e32 v1, 2, v1
	ds_bpermute_b32 v1, v1, v0
	v_cmp_lt_i32_e32 vcc, v189, v187
	s_waitcnt lgkmcnt(0)
	v_add_f32_e32 v0, v0, v1
	v_cndmask_b32_e32 v1, v185, v189, vcc
	v_lshlrev_b32_e32 v1, 2, v1
	ds_bpermute_b32 v1, v1, v0
	v_cmp_lt_i32_e32 vcc, v190, v187
	s_waitcnt lgkmcnt(0)
	v_add_f32_e32 v0, v0, v1
	v_cndmask_b32_e32 v1, v185, v190, vcc
	v_lshlrev_b32_e32 v1, 2, v1
	ds_bpermute_b32 v1, v1, v0
	s_waitcnt lgkmcnt(0)
	v_add_f32_e32 v0, v0, v1
	v_fmamk_f32 v0, v0, 0x3b000000, v182
	v_cmp_gt_f32_e32 vcc, s56, v0
	v_mul_f32_e32 v1, 0x4b800000, v0
	s_nop 0
	v_cndmask_b32_e32 v0, v0, v1, vcc
	v_rsq_f32_e32 v0, v0
	s_nop 0
	v_mul_f32_e32 v1, 0x45800000, v0
	v_cndmask_b32_e32 v16, v0, v1, vcc
	global_load_dwordx4 v[74:77], v32, s[0:1] offset:16
	global_load_dwordx4 v[78:81], v32, s[0:1]
	global_load_dwordx4 v[82:85], v32, s[0:1] offset:272
	global_load_dwordx4 v[86:89], v32, s[0:1] offset:256
	global_load_dwordx4 v[90:93], v32, s[0:1] offset:528
	global_load_dwordx4 v[94:97], v32, s[0:1] offset:512
	global_load_dwordx4 v[98:101], v32, s[0:1] offset:784
	global_load_dwordx4 v[102:105], v32, s[0:1] offset:768
	global_load_dwordx4 v[110:113], v32, s[0:1] offset:1040
	global_load_dwordx4 v[114:117], v32, s[0:1] offset:1024
	global_load_dwordx4 v[118:121], v32, s[0:1] offset:1296
	global_load_dwordx4 v[122:125], v32, s[0:1] offset:1280
	global_load_dwordx4 v[126:129], v32, s[0:1] offset:1552
	global_load_dwordx4 v[134:137], v32, s[0:1] offset:1536
	global_load_dwordx4 v[138:141], v32, s[0:1] offset:1808
	global_load_dwordx4 v[142:145], v32, s[0:1] offset:1792
	v_mul_f32_e32 v73, v73, v16
	v_mul_f32_e32 v69, v69, v16
	v_mul_f32_e32 v68, v68, v16
	v_mul_f32_e32 v67, v67, v16
	v_mul_f32_e32 v72, v72, v16
	v_mul_f32_e32 v71, v71, v16
	v_mul_f32_e32 v70, v70, v16
	v_mul_f32_e32 v51, v51, v16
	v_mul_f32_e32 v60, v60, v16
	v_mul_f32_e32 v56, v56, v16
	v_mul_f32_e32 v20, v20, v16
	v_mul_f32_e32 v22, v22, v16
	v_mul_f32_e32 v21, v21, v16
	v_mul_f32_e32 v10, v10, v16
	v_mul_f32_e32 v12, v12, v16
	v_mul_f32_e32 v13, v13, v16
	s_waitcnt vmcnt(15)
	v_mul_f32_e32 v0, v74, v69
	s_waitcnt vmcnt(14)
	v_mul_f32_e32 v4, v78, v73
	v_mul_f32_e32 v1, v75, v68
	v_mul_f32_e32 v67, v76, v67
	v_mul_f32_e32 v2, v65, v16
	v_mul_f32_e32 v5, v79, v72
	v_mul_f32_e32 v65, v77, v2
	v_cvt_pk_bf16_f32 v2, v4, v5
	v_cvt_pk_bf16_f32 v4, v0, v1
	v_lshl_add_u64 v[0:1], s[8:9], 0, v[108:109]
	v_lshl_add_u64 v[0:1], v[0:1], 0, s[28:29]
	v_lshl_add_u64 v[0:1], v[0:1], 0, v[132:133]
	v_mul_f32_e32 v6, v80, v71
	v_mul_f32_e32 v7, v81, v70
	v_cvt_pk_bf16_f32 v3, v6, v7
	v_cvt_pk_bf16_f32 v5, v67, v65
	global_store_dwordx4 v[0:1], v[2:5], off
	v_mul_f32_e32 v6, v66, v16
	v_mul_f32_e32 v7, v63, v16
	s_waitcnt vmcnt(14)
	v_mul_f32_e32 v51, v51, v82
	v_mul_f32_e32 v2, v45, v16
	v_mul_f32_e32 v45, v2, v83
	v_mul_f32_e32 v2, v40, v16
	v_mul_f32_e32 v40, v2, v84
	v_mul_f32_e32 v2, v35, v16
	v_mul_f32_e32 v5, v2, v85
	s_waitcnt vmcnt(13)
	v_mul_f32_e32 v6, v6, v86
	v_mul_f32_e32 v7, v7, v87
	v_mul_f32_e32 v60, v60, v88
	v_mul_f32_e32 v56, v56, v89
	v_cvt_pk_bf16_f32 v2, v6, v7
	v_cvt_pk_bf16_f32 v3, v60, v56
	v_cvt_pk_bf16_f32 v4, v51, v45
	v_cvt_pk_bf16_f32 v5, v40, v5
	global_store_dwordx4 v[0:1], v[2:5], off offset:128
	v_mul_f32_e32 v45, v46, v16
	v_mul_f32_e32 v6, v64, v16
	v_mul_f32_e32 v7, v61, v16
	v_mul_f32_e32 v35, v57, v16
	v_mul_f32_e32 v40, v52, v16
	s_waitcnt vmcnt(13)
	v_mul_f32_e32 v45, v45, v90
	v_mul_f32_e32 v2, v41, v16
	v_mul_f32_e32 v41, v2, v91
	v_mul_f32_e32 v2, v36, v16
	v_mul_f32_e32 v36, v2, v92
	v_mul_f32_e32 v2, v30, v16
	v_mul_f32_e32 v5, v2, v93
	s_waitcnt vmcnt(12)
	v_mul_f32_e32 v6, v6, v94
	v_mul_f32_e32 v7, v7, v95
	v_mul_f32_e32 v35, v35, v96
	v_mul_f32_e32 v40, v40, v97
	v_cvt_pk_bf16_f32 v2, v6, v7
	v_cvt_pk_bf16_f32 v3, v35, v40
	v_cvt_pk_bf16_f32 v4, v45, v41
	v_cvt_pk_bf16_f32 v5, v36, v5
	global_store_dwordx4 v[0:1], v[2:5], off offset:256
	v_mul_f32_e32 v36, v42, v16
	v_mul_f32_e32 v6, v62, v16
	v_mul_f32_e32 v7, v58, v16
	v_mul_f32_e32 v30, v53, v16
	v_mul_f32_e32 v35, v47, v16
	s_waitcnt vmcnt(12)
	v_mul_f32_e32 v36, v36, v98
	v_mul_f32_e32 v2, v37, v16
	v_mul_f32_e32 v37, v2, v99
	v_mul_f32_e32 v2, v31, v16
	v_mul_f32_e32 v31, v2, v100
	v_mul_f32_e32 v2, v27, v16
	v_mul_f32_e32 v5, v2, v101
	s_waitcnt vmcnt(11)
	v_mul_f32_e32 v6, v6, v102
	v_mul_f32_e32 v7, v7, v103
	v_mul_f32_e32 v30, v30, v104
	v_mul_f32_e32 v35, v35, v105
	v_cvt_pk_bf16_f32 v2, v6, v7
	v_cvt_pk_bf16_f32 v3, v30, v35
	v_cvt_pk_bf16_f32 v4, v36, v37
	v_cvt_pk_bf16_f32 v5, v31, v5
	global_store_dwordx4 v[0:1], v[2:5], off offset:384
	v_mul_f32_e32 v31, v38, v16
	v_mul_f32_e32 v6, v59, v16
	v_mul_f32_e32 v7, v54, v16
	v_mul_f32_e32 v27, v48, v16
	v_mul_f32_e32 v30, v43, v16
	s_waitcnt vmcnt(11)
	v_mul_f32_e32 v31, v31, v110
	v_mul_f32_e32 v2, v33, v16
	v_mul_f32_e32 v33, v2, v111
	v_mul_f32_e32 v2, v28, v16
	v_mul_f32_e32 v28, v2, v112
	v_mul_f32_e32 v2, v24, v16
	v_mul_f32_e32 v5, v2, v113
	s_waitcnt vmcnt(10)
	v_mul_f32_e32 v6, v6, v114
	v_mul_f32_e32 v7, v7, v115
	v_mul_f32_e32 v27, v27, v116
	v_mul_f32_e32 v30, v30, v117
	v_cvt_pk_bf16_f32 v2, v6, v7
	v_cvt_pk_bf16_f32 v3, v27, v30
	v_cvt_pk_bf16_f32 v4, v31, v33
	v_cvt_pk_bf16_f32 v5, v28, v5
	global_store_dwordx4 v[0:1], v[2:5], off offset:512
	v_mul_f32_e32 v28, v34, v16
	v_mul_f32_e32 v6, v55, v16
	v_mul_f32_e32 v7, v49, v16
	v_mul_f32_e32 v24, v44, v16
	v_mul_f32_e32 v27, v39, v16
	s_waitcnt vmcnt(10)
	v_mul_f32_e32 v28, v28, v118
	v_mul_f32_e32 v2, v29, v16
	v_mul_f32_e32 v29, v2, v119
	v_mul_f32_e32 v2, v25, v16
	v_mul_f32_e32 v25, v2, v120
	v_mul_f32_e32 v2, v23, v16
	v_mul_f32_e32 v5, v2, v121
	s_waitcnt vmcnt(9)
	v_mul_f32_e32 v6, v6, v122
	v_mul_f32_e32 v7, v7, v123
	v_mul_f32_e32 v24, v24, v124
	v_mul_f32_e32 v27, v27, v125
	v_cvt_pk_bf16_f32 v2, v6, v7
	v_cvt_pk_bf16_f32 v3, v24, v27
	v_cvt_pk_bf16_f32 v4, v28, v29
	v_cvt_pk_bf16_f32 v5, v25, v5
	global_store_dwordx4 v[0:1], v[2:5], off offset:640
	v_mul_f32_e32 v6, v50, v16
	v_mul_f32_e32 v7, v26, v16
	s_waitcnt vmcnt(9)
	v_mul_f32_e32 v20, v20, v126
	v_mul_f32_e32 v2, v19, v16
	v_mul_f32_e32 v19, v2, v127
	v_mul_f32_e32 v2, v18, v16
	v_mul_f32_e32 v18, v2, v128
	v_mul_f32_e32 v2, v17, v16
	v_mul_f32_e32 v5, v2, v129
	s_waitcnt vmcnt(8)
	v_mul_f32_e32 v6, v6, v134
	v_mul_f32_e32 v7, v7, v135
	v_mul_f32_e32 v22, v22, v136
	v_mul_f32_e32 v21, v21, v137
	v_cvt_pk_bf16_f32 v2, v6, v7
	v_cvt_pk_bf16_f32 v3, v22, v21
	v_cvt_pk_bf16_f32 v4, v20, v19
	v_cvt_pk_bf16_f32 v5, v18, v5
	global_store_dwordx4 v[0:1], v[2:5], off offset:768
	v_mul_f32_e32 v6, v14, v16
	v_mul_f32_e32 v7, v15, v16
	s_mov_b64 s[0:1], 0
	s_waitcnt vmcnt(8)
	v_mul_f32_e32 v10, v10, v138
	v_mul_f32_e32 v2, v11, v16
	v_mul_f32_e32 v11, v2, v139
	v_mul_f32_e32 v2, v8, v16
	v_mul_f32_e32 v8, v2, v140
	v_mul_f32_e32 v2, v9, v16
	v_mul_f32_e32 v5, v2, v141
	s_waitcnt vmcnt(7)
	v_mul_f32_e32 v6, v6, v142
	v_mul_f32_e32 v7, v7, v143
	v_mul_f32_e32 v12, v12, v144
	v_mul_f32_e32 v13, v13, v145
	v_cvt_pk_bf16_f32 v2, v6, v7
	v_cvt_pk_bf16_f32 v3, v12, v13
	v_cvt_pk_bf16_f32 v4, v10, v11
	v_cvt_pk_bf16_f32 v5, v8, v5
	global_store_dwordx4 v[0:1], v[2:5], off offset:896
	s_barrier
